# GEMM1 merge-gate epilogue: packed sigmoid (pk_fma with pre-scaled bias, pk_add), 792 -> 500 lines
# speedup vs baseline: 1.0038x; 1.0035x over previous
.LBB0_188:
	ds_read_b128 v[130:133], v178
	ds_read_b128 v[134:137], v178 offset:1024
	ds_read_b128 v[138:141], v178 offset:2048
	ds_read_b128 v[142:145], v178 offset:3072
	s_add_u32 s15, s34, 0xfffc0080
	s_addc_u32 s16, s35, -1
	s_cmp_eq_u32 s14, 12
	s_cselect_b32 s39, s25, s16
	s_cselect_b32 s38, s31, s15
	s_cselect_b32 s37, s23, vcc_hi
	s_cselect_b32 s36, s90, vcc_lo
	v_lshl_add_u64 v[206:207], s[34:35], 0, v[164:165]
	s_add_i32 m0, s68, 0xc000
	ds_read_b128 v[146:149], v179
	ds_read_b128 v[174:177], v179 offset:1024
	ds_read_b128 v[182:185], v179 offset:2048
	ds_read_b128 v[186:189], v179 offset:3072
	ds_read_b128 v[190:193], v179 offset:4096
	ds_read_b128 v[194:197], v179 offset:5120
	ds_read_b128 v[198:201], v179 offset:6144
	ds_read_b128 v[202:205], v179 offset:7168
	global_load_lds_dwordx4 v[206:207], off
	v_lshl_add_u64 v[206:207], s[34:35], 0, v[166:167]
	s_add_i32 m0, s68, 0xe000
	s_nop 0
	global_load_lds_dwordx4 v[206:207], off
	s_waitcnt lgkmcnt(8)
	s_barrier
	s_waitcnt lgkmcnt(0)
	s_setprio 1
	s_waitcnt lgkmcnt(0)
	v_mfma_f32_16x16x32_bf16 v[126:129], v[130:133], v[146:149], v[126:129]
	v_mfma_f32_16x16x32_bf16 v[122:125], v[138:141], v[146:149], v[122:125]
	v_mfma_f32_16x16x32_bf16 v[110:113], v[130:133], v[182:185], v[110:113]
	v_mfma_f32_16x16x32_bf16 v[106:109], v[138:141], v[182:185], v[106:109]
	v_mfma_f32_16x16x32_bf16 v[94:97], v[130:133], v[190:193], v[94:97]
	v_mfma_f32_16x16x32_bf16 v[90:93], v[138:141], v[190:193], v[90:93]
	v_mfma_f32_16x16x32_bf16 v[78:81], v[130:133], v[198:201], v[78:81]
	v_mfma_f32_16x16x32_bf16 v[74:77], v[138:141], v[198:201], v[74:77]
	v_mfma_f32_16x16x32_bf16 v[126:129], v[134:137], v[174:177], v[126:129]
	v_mfma_f32_16x16x32_bf16 v[122:125], v[142:145], v[174:177], v[122:125]
	v_mfma_f32_16x16x32_bf16 v[110:113], v[134:137], v[186:189], v[110:113]
	v_mfma_f32_16x16x32_bf16 v[106:109], v[142:145], v[186:189], v[106:109]
	v_mfma_f32_16x16x32_bf16 v[94:97], v[134:137], v[194:197], v[94:97]
	v_mfma_f32_16x16x32_bf16 v[90:93], v[142:145], v[194:197], v[90:93]
	v_mfma_f32_16x16x32_bf16 v[78:81], v[134:137], v[202:205], v[78:81]
	v_mfma_f32_16x16x32_bf16 v[74:77], v[142:145], v[202:205], v[74:77]
	s_setprio 0
	s_barrier
	s_add_i32 s15, s13, s41
	v_lshl_add_u64 v[222:223], s[36:37], 0, v[152:153]
	s_mov_b32 m0, s15
	ds_read_b128 v[206:209], v180
	ds_read_b128 v[210:213], v180 offset:1024
	ds_read_b128 v[214:217], v180 offset:2048
	ds_read_b128 v[218:221], v180 offset:3072
	global_load_lds_dwordx4 v[222:223], off
	v_lshl_add_u64 v[224:225], s[36:37], 0, v[156:157]
	s_add_i32 m0, s15, 0x2000
	s_nop 0
	global_load_lds_dwordx4 v[224:225], off
	s_barrier
	s_waitcnt lgkmcnt(0)
	s_setprio 1
	s_waitcnt lgkmcnt(0)
	v_mfma_f32_16x16x32_bf16 v[118:121], v[206:209], v[146:149], v[118:121]
	v_mfma_f32_16x16x32_bf16 v[114:117], v[214:217], v[146:149], v[114:117]
	v_mfma_f32_16x16x32_bf16 v[102:105], v[206:209], v[182:185], v[102:105]
	v_mfma_f32_16x16x32_bf16 v[98:101], v[214:217], v[182:185], v[98:101]
	v_mfma_f32_16x16x32_bf16 v[86:89], v[206:209], v[190:193], v[86:89]
	v_mfma_f32_16x16x32_bf16 v[82:85], v[214:217], v[190:193], v[82:85]
	v_mfma_f32_16x16x32_bf16 v[70:73], v[206:209], v[198:201], v[70:73]
	v_mfma_f32_16x16x32_bf16 v[66:69], v[214:217], v[198:201], v[66:69]
	v_mfma_f32_16x16x32_bf16 v[118:121], v[210:213], v[174:177], v[118:121]
	v_mfma_f32_16x16x32_bf16 v[114:117], v[218:221], v[174:177], v[114:117]
	v_mfma_f32_16x16x32_bf16 v[102:105], v[210:213], v[186:189], v[102:105]
	v_mfma_f32_16x16x32_bf16 v[98:101], v[218:221], v[186:189], v[98:101]
	v_mfma_f32_16x16x32_bf16 v[86:89], v[210:213], v[194:197], v[86:89]
	v_mfma_f32_16x16x32_bf16 v[82:85], v[218:221], v[194:197], v[82:85]
	v_mfma_f32_16x16x32_bf16 v[70:73], v[210:213], v[202:205], v[70:73]
	v_mfma_f32_16x16x32_bf16 v[66:69], v[218:221], v[202:205], v[66:69]
	s_setprio 0
	s_mov_b32 m0, s68
	v_lshl_add_u64 v[226:227], s[38:39], 0, v[150:151]
	s_barrier
	ds_read_b128 v[146:149], v179 offset:16384
	ds_read_b128 v[174:177], v179 offset:17408
	ds_read_b128 v[182:185], v179 offset:18432
	ds_read_b128 v[186:189], v179 offset:19456
	ds_read_b128 v[190:193], v179 offset:20480
	ds_read_b128 v[194:197], v179 offset:21504
	ds_read_b128 v[198:201], v179 offset:22528
	ds_read_b128 v[202:205], v179 offset:23552
	global_load_lds_dwordx4 v[226:227], off
	v_lshl_add_u64 v[228:229], s[38:39], 0, v[154:155]
	s_mov_b32 m0, s69
	s_nop 0
	global_load_lds_dwordx4 v[228:229], off
	s_barrier
	s_waitcnt lgkmcnt(0)
	s_setprio 1
	s_waitcnt lgkmcnt(0)
	v_mfma_f32_16x16x32_bf16 v[62:65], v[130:133], v[146:149], v[62:65]
	v_mfma_f32_16x16x32_bf16 v[58:61], v[138:141], v[146:149], v[58:61]
	v_mfma_f32_16x16x32_bf16 v[46:49], v[130:133], v[182:185], v[46:49]
	v_mfma_f32_16x16x32_bf16 v[42:45], v[138:141], v[182:185], v[42:45]
	v_mfma_f32_16x16x32_bf16 v[30:33], v[130:133], v[190:193], v[30:33]
	v_mfma_f32_16x16x32_bf16 v[26:29], v[138:141], v[190:193], v[26:29]
	v_mfma_f32_16x16x32_bf16 v[14:17], v[130:133], v[198:201], v[14:17]
	v_mfma_f32_16x16x32_bf16 v[10:13], v[138:141], v[198:201], v[10:13]
	v_mfma_f32_16x16x32_bf16 v[62:65], v[134:137], v[174:177], v[62:65]
	v_mfma_f32_16x16x32_bf16 v[58:61], v[142:145], v[174:177], v[58:61]
	v_mfma_f32_16x16x32_bf16 v[46:49], v[134:137], v[186:189], v[46:49]
	v_mfma_f32_16x16x32_bf16 v[42:45], v[142:145], v[186:189], v[42:45]
	v_mfma_f32_16x16x32_bf16 v[30:33], v[134:137], v[194:197], v[30:33]
	v_mfma_f32_16x16x32_bf16 v[26:29], v[142:145], v[194:197], v[26:29]
	v_mfma_f32_16x16x32_bf16 v[14:17], v[134:137], v[202:205], v[14:17]
	v_mfma_f32_16x16x32_bf16 v[10:13], v[142:145], v[202:205], v[10:13]
	s_setprio 0
	s_barrier
	s_add_u32 s16, s36, 0x40000
	s_addc_u32 s17, s37, 0
	s_add_i32 s15, s88, s41
	v_lshl_add_u64 v[130:131], s[16:17], 0, v[152:153]
	s_mov_b32 m0, s15
	s_nop 0
	global_load_lds_dwordx4 v[130:131], off
	v_lshl_add_u64 v[130:131], s[16:17], 0, v[156:157]
	s_add_i32 m0, s15, 0x2000
	s_nop 0
	global_load_lds_dwordx4 v[130:131], off
	s_waitcnt vmcnt(6)
	s_barrier
	s_setprio 1
	v_mfma_f32_16x16x32_bf16 v[54:57], v[206:209], v[146:149], v[54:57]
	v_mfma_f32_16x16x32_bf16 v[50:53], v[214:217], v[146:149], v[50:53]
	v_mfma_f32_16x16x32_bf16 v[38:41], v[206:209], v[182:185], v[38:41]
	v_mfma_f32_16x16x32_bf16 v[34:37], v[214:217], v[182:185], v[34:37]
	v_mfma_f32_16x16x32_bf16 v[22:25], v[206:209], v[190:193], v[22:25]
	v_mfma_f32_16x16x32_bf16 v[18:21], v[214:217], v[190:193], v[18:21]
	v_mfma_f32_16x16x32_bf16 v[6:9], v[206:209], v[198:201], v[6:9]
	v_mfma_f32_16x16x32_bf16 v[2:5], v[214:217], v[198:201], v[2:5]
	v_mfma_f32_16x16x32_bf16 v[54:57], v[210:213], v[174:177], v[54:57]
	v_mfma_f32_16x16x32_bf16 v[50:53], v[218:221], v[174:177], v[50:53]
	v_mfma_f32_16x16x32_bf16 v[38:41], v[210:213], v[186:189], v[38:41]
	v_mfma_f32_16x16x32_bf16 v[34:37], v[218:221], v[186:189], v[34:37]
	v_mfma_f32_16x16x32_bf16 v[22:25], v[210:213], v[194:197], v[22:25]
	v_mfma_f32_16x16x32_bf16 v[18:21], v[218:221], v[194:197], v[18:21]
	v_mfma_f32_16x16x32_bf16 v[6:9], v[210:213], v[202:205], v[6:9]
	v_mfma_f32_16x16x32_bf16 v[2:5], v[218:221], v[202:205], v[2:5]
	s_setprio 0
	s_add_i32 s15, 0, 0x18000
	v_add_u32_e32 v142, s15, v161
	s_barrier
	ds_read_b128 v[130:133], v142
	ds_read_b128 v[134:137], v142 offset:1024
	ds_read_b128 v[138:141], v142 offset:2048
	ds_read_b128 v[142:145], v142 offset:3072
	s_add_u32 s16, s38, 0x40000
	s_addc_u32 s17, s39, 0
	s_mov_b32 m0, s84
	v_lshl_add_u64 v[206:207], s[16:17], 0, v[150:151]
	ds_read_b128 v[146:149], v179 offset:32768
	ds_read_b128 v[174:177], v179 offset:33792
	ds_read_b128 v[182:185], v179 offset:34816
	ds_read_b128 v[186:189], v179 offset:35840
	ds_read_b128 v[190:193], v179 offset:36864
	ds_read_b128 v[194:197], v179 offset:37888
	ds_read_b128 v[198:201], v179 offset:38912
	ds_read_b128 v[202:205], v179 offset:39936
	global_load_lds_dwordx4 v[206:207], off
	v_lshl_add_u64 v[206:207], s[16:17], 0, v[154:155]
	s_mov_b32 m0, s85
	s_nop 0
	global_load_lds_dwordx4 v[206:207], off
	s_waitcnt lgkmcnt(8)
	s_barrier
	s_waitcnt lgkmcnt(0)
	s_setprio 1
	s_waitcnt lgkmcnt(0)
	v_mfma_f32_16x16x32_bf16 v[126:129], v[130:133], v[146:149], v[126:129]
	v_mfma_f32_16x16x32_bf16 v[122:125], v[138:141], v[146:149], v[122:125]
	v_mfma_f32_16x16x32_bf16 v[110:113], v[130:133], v[182:185], v[110:113]
	v_mfma_f32_16x16x32_bf16 v[106:109], v[138:141], v[182:185], v[106:109]
	v_mfma_f32_16x16x32_bf16 v[94:97], v[130:133], v[190:193], v[94:97]
	v_mfma_f32_16x16x32_bf16 v[90:93], v[138:141], v[190:193], v[90:93]
	v_mfma_f32_16x16x32_bf16 v[78:81], v[130:133], v[198:201], v[78:81]
	v_mfma_f32_16x16x32_bf16 v[74:77], v[138:141], v[198:201], v[74:77]
	v_mfma_f32_16x16x32_bf16 v[126:129], v[134:137], v[174:177], v[126:129]
	v_mfma_f32_16x16x32_bf16 v[122:125], v[142:145], v[174:177], v[122:125]
	v_mfma_f32_16x16x32_bf16 v[110:113], v[134:137], v[186:189], v[110:113]
	v_mfma_f32_16x16x32_bf16 v[106:109], v[142:145], v[186:189], v[106:109]
	v_mfma_f32_16x16x32_bf16 v[94:97], v[134:137], v[194:197], v[94:97]
	v_mfma_f32_16x16x32_bf16 v[90:93], v[142:145], v[194:197], v[90:93]
	v_mfma_f32_16x16x32_bf16 v[78:81], v[134:137], v[202:205], v[78:81]
	v_mfma_f32_16x16x32_bf16 v[74:77], v[142:145], v[202:205], v[74:77]
	s_setprio 0
	s_barrier
	s_add_i32 s38, 0, 0x1c000
	s_add_i32 s15, s15, s41
	v_add_u32_e32 v158, s38, v161
	v_lshl_add_u64 v[222:223], v[222:223], 0, s[10:11]
	s_mov_b32 m0, s15
	ds_read_b128 v[206:209], v158
	ds_read_b128 v[210:213], v158 offset:1024
	ds_read_b128 v[214:217], v158 offset:2048
	ds_read_b128 v[218:221], v158 offset:3072
	global_load_lds_dwordx4 v[222:223], off
	v_lshl_add_u64 v[222:223], v[224:225], 0, s[10:11]
	s_add_i32 m0, s15, 0x2000
	s_nop 0
	global_load_lds_dwordx4 v[222:223], off
	s_barrier
	s_waitcnt lgkmcnt(0)
	s_setprio 1
	s_waitcnt lgkmcnt(0)
	v_mfma_f32_16x16x32_bf16 v[118:121], v[206:209], v[146:149], v[118:121]
	v_mfma_f32_16x16x32_bf16 v[114:117], v[214:217], v[146:149], v[114:117]
	v_mfma_f32_16x16x32_bf16 v[102:105], v[206:209], v[182:185], v[102:105]
	v_mfma_f32_16x16x32_bf16 v[98:101], v[214:217], v[182:185], v[98:101]
	v_mfma_f32_16x16x32_bf16 v[86:89], v[206:209], v[190:193], v[86:89]
	v_mfma_f32_16x16x32_bf16 v[82:85], v[214:217], v[190:193], v[82:85]
	v_mfma_f32_16x16x32_bf16 v[70:73], v[206:209], v[198:201], v[70:73]
	v_mfma_f32_16x16x32_bf16 v[66:69], v[214:217], v[198:201], v[66:69]
	v_mfma_f32_16x16x32_bf16 v[118:121], v[210:213], v[174:177], v[118:121]
	v_mfma_f32_16x16x32_bf16 v[114:117], v[218:221], v[174:177], v[114:117]
	v_mfma_f32_16x16x32_bf16 v[102:105], v[210:213], v[186:189], v[102:105]
	v_mfma_f32_16x16x32_bf16 v[98:101], v[218:221], v[186:189], v[98:101]
	v_mfma_f32_16x16x32_bf16 v[86:89], v[210:213], v[194:197], v[86:89]
	v_mfma_f32_16x16x32_bf16 v[82:85], v[218:221], v[194:197], v[82:85]
	v_mfma_f32_16x16x32_bf16 v[70:73], v[210:213], v[202:205], v[70:73]
	v_mfma_f32_16x16x32_bf16 v[66:69], v[218:221], v[202:205], v[66:69]
	s_setprio 0
	s_mov_b32 m0, s97
	v_lshl_add_u64 v[222:223], v[226:227], 0, s[10:11]
	s_barrier
	ds_read_b128 v[146:149], v179 offset:49152
	ds_read_b128 v[174:177], v179 offset:50176
	ds_read_b128 v[182:185], v179 offset:51200
	ds_read_b128 v[186:189], v179 offset:52224
	ds_read_b128 v[190:193], v179 offset:53248
	ds_read_b128 v[194:197], v179 offset:54272
	ds_read_b128 v[198:201], v179 offset:55296
	ds_read_b128 v[202:205], v179 offset:56320
	global_load_lds_dwordx4 v[222:223], off
	v_lshl_add_u64 v[222:223], v[228:229], 0, s[10:11]
	s_mov_b32 m0, s91
	s_nop 0
	global_load_lds_dwordx4 v[222:223], off
	s_barrier
	s_waitcnt lgkmcnt(0)
	s_setprio 1
	s_waitcnt lgkmcnt(0)
	v_mfma_f32_16x16x32_bf16 v[62:65], v[130:133], v[146:149], v[62:65]
	v_mfma_f32_16x16x32_bf16 v[58:61], v[138:141], v[146:149], v[58:61]
	v_mfma_f32_16x16x32_bf16 v[46:49], v[130:133], v[182:185], v[46:49]
	v_mfma_f32_16x16x32_bf16 v[42:45], v[138:141], v[182:185], v[42:45]
	v_mfma_f32_16x16x32_bf16 v[30:33], v[130:133], v[190:193], v[30:33]
	v_mfma_f32_16x16x32_bf16 v[26:29], v[138:141], v[190:193], v[26:29]
	v_mfma_f32_16x16x32_bf16 v[14:17], v[130:133], v[198:201], v[14:17]
	v_mfma_f32_16x16x32_bf16 v[10:13], v[138:141], v[198:201], v[10:13]
	v_mfma_f32_16x16x32_bf16 v[62:65], v[134:137], v[174:177], v[62:65]
	v_mfma_f32_16x16x32_bf16 v[58:61], v[142:145], v[174:177], v[58:61]
	v_mfma_f32_16x16x32_bf16 v[46:49], v[134:137], v[186:189], v[46:49]
	v_mfma_f32_16x16x32_bf16 v[42:45], v[142:145], v[186:189], v[42:45]
	v_mfma_f32_16x16x32_bf16 v[30:33], v[134:137], v[194:197], v[30:33]
	v_mfma_f32_16x16x32_bf16 v[26:29], v[142:145], v[194:197], v[26:29]
	v_mfma_f32_16x16x32_bf16 v[14:17], v[134:137], v[202:205], v[14:17]
	v_mfma_f32_16x16x32_bf16 v[10:13], v[142:145], v[202:205], v[10:13]
	s_setprio 0
	s_barrier
	s_add_u32 s16, s36, 0x40080
	s_addc_u32 s17, s37, 0
	s_add_i32 s15, s38, s41
	v_lshl_add_u64 v[130:131], s[16:17], 0, v[152:153]
	s_mov_b32 m0, s15
	s_nop 0
	global_load_lds_dwordx4 v[130:131], off
	v_lshl_add_u64 v[130:131], s[16:17], 0, v[156:157]
	s_add_i32 m0, s15, 0x2000
	s_nop 0
	global_load_lds_dwordx4 v[130:131], off
	s_waitcnt vmcnt(6)
	s_barrier
	s_setprio 1
	v_mfma_f32_16x16x32_bf16 v[54:57], v[206:209], v[146:149], v[54:57]
	v_mfma_f32_16x16x32_bf16 v[50:53], v[214:217], v[146:149], v[50:53]
	v_mfma_f32_16x16x32_bf16 v[38:41], v[206:209], v[182:185], v[38:41]
	v_mfma_f32_16x16x32_bf16 v[34:37], v[214:217], v[182:185], v[34:37]
	v_mfma_f32_16x16x32_bf16 v[22:25], v[206:209], v[190:193], v[22:25]
	v_mfma_f32_16x16x32_bf16 v[18:21], v[214:217], v[190:193], v[18:21]
	v_mfma_f32_16x16x32_bf16 v[6:9], v[206:209], v[198:201], v[6:9]
	v_mfma_f32_16x16x32_bf16 v[2:5], v[214:217], v[198:201], v[2:5]
	v_mfma_f32_16x16x32_bf16 v[54:57], v[210:213], v[174:177], v[54:57]
	v_mfma_f32_16x16x32_bf16 v[50:53], v[218:221], v[174:177], v[50:53]
	v_mfma_f32_16x16x32_bf16 v[38:41], v[210:213], v[186:189], v[38:41]
	v_mfma_f32_16x16x32_bf16 v[34:37], v[218:221], v[186:189], v[34:37]
	v_mfma_f32_16x16x32_bf16 v[22:25], v[210:213], v[194:197], v[22:25]
	v_mfma_f32_16x16x32_bf16 v[18:21], v[218:221], v[194:197], v[18:21]
	v_mfma_f32_16x16x32_bf16 v[6:9], v[210:213], v[202:205], v[6:9]
	v_mfma_f32_16x16x32_bf16 v[2:5], v[218:221], v[202:205], v[2:5]
	s_setprio 0
	s_add_i32 s14, s14, 2
	s_add_u32 s34, s34, 0x100
	s_addc_u32 s35, s35, 0
	s_add_u32 vcc_lo, vcc_lo, 0x100
	s_addc_u32 vcc_hi, vcc_hi, 0
	s_cmp_gt_u32 s14, 13
	s_barrier
	s_cbranch_scc0 .LBB0_188
	v_lshl_add_u32 v174, s30, 8, v1
	s_cmp_gt_i32 s12, 3
	s_mov_b64 s[34:35], -1
	s_cbranch_scc0 .LBB0_204
	s_cmp_gt_u32 s12, 7
	s_cbranch_scc0 .LBB0_201
	s_cmp_lt_u32 s12, 16
	s_cbranch_scc0 .LBB0_193
	s_add_i32 s14, s12, -8
	v_lshl_or_b32 v158, s14, 8, v160
	v_lshl_add_u64 v[134:135], v[158:159], 2, s[70:71]
	global_load_dwordx4 v[138:141], v[134:135], off offset:16
	global_load_dwordx4 v[142:145], v[134:135], off
	global_load_dwordx4 v[130:133], v[134:135], off offset:528
	s_nop 0
	global_load_dwordx4 v[134:137], v[134:135], off offset:512
	s_lshl_b32 s15, s30, 3
	s_add_i32 s14, s15, s14
	s_ashr_i32 s15, s14, 31
	s_lshl_b64 s[14:15], s[14:15], 17
	v_readlane_b32 s16, v254, 9
	s_add_u32 s30, s16, s14
	v_readlane_b32 s14, v254, 10
	s_addc_u32 s31, s14, s15
	v_mov_b32_e32 v173, v159
	v_lshl_add_u64 v[176:177], s[30:31], 0, v[172:173]
	s_mov_b64 s[34:35], 0
	s_mov_b32 s14, 0x1000
	s_mov_b32 s15, 0
	s_mov_b32 s100, 0xbfb8aa3b
	s_mov_b32 s101, 0xbfb8aa3b
	s_waitcnt vmcnt(0)
	v_pk_mul_f32 v[130:131], v[130:131], s[100:101]
	v_pk_mul_f32 v[132:133], v[132:133], s[100:101]
	v_pk_mul_f32 v[134:135], v[134:135], s[100:101]
	v_pk_mul_f32 v[136:137], v[136:137], s[100:101]
	v_pk_mul_f32 v[138:139], v[138:139], s[100:101]
	v_pk_mul_f32 v[140:141], v[140:141], s[100:101]
	v_pk_mul_f32 v[142:143], v[142:143], s[100:101]
	v_pk_mul_f32 v[144:145], v[144:145], s[100:101]
	v_pk_fma_f32 v[126:127], v[126:127], s[100:101], v[142:143]
	v_pk_fma_f32 v[128:129], v[128:129], s[100:101], v[144:145]
	v_pk_fma_f32 v[122:123], v[122:123], s[100:101], v[138:139]
	v_pk_fma_f32 v[124:125], v[124:125], s[100:101], v[140:141]
	v_exp_f32_e32 v126, v126
	v_exp_f32_e32 v127, v127
	v_exp_f32_e32 v128, v128
	v_exp_f32_e32 v129, v129
	v_exp_f32_e32 v122, v122
	v_exp_f32_e32 v123, v123
	v_exp_f32_e32 v124, v124
	v_exp_f32_e32 v125, v125
	v_pk_add_f32 v[126:127], v[126:127], 1.0 op_sel_hi:[1,0]
	v_pk_add_f32 v[128:129], v[128:129], 1.0 op_sel_hi:[1,0]
	v_pk_add_f32 v[122:123], v[122:123], 1.0 op_sel_hi:[1,0]
	v_pk_add_f32 v[124:125], v[124:125], 1.0 op_sel_hi:[1,0]
	v_rcp_f32_e32 v126, v126
	v_rcp_f32_e32 v127, v127
	v_rcp_f32_e32 v128, v128
	v_rcp_f32_e32 v129, v129
	v_rcp_f32_e32 v122, v122
	v_rcp_f32_e32 v123, v123
	v_rcp_f32_e32 v124, v124
	v_rcp_f32_e32 v125, v125
	v_cvt_pk_bf16_f32 v146, v126, v127
	v_cvt_pk_bf16_f32 v147, v128, v129
	v_cvt_pk_bf16_f32 v148, v122, v123
	v_cvt_pk_bf16_f32 v149, v124, v125
	global_store_dwordx4 v[176:177], v[146:149], off offset:0
	v_pk_fma_f32 v[118:119], v[118:119], s[100:101], v[134:135]
	v_pk_fma_f32 v[120:121], v[120:121], s[100:101], v[136:137]
	v_pk_fma_f32 v[114:115], v[114:115], s[100:101], v[130:131]
	v_pk_fma_f32 v[116:117], v[116:117], s[100:101], v[132:133]
	v_exp_f32_e32 v118, v118
	v_exp_f32_e32 v119, v119
	v_exp_f32_e32 v120, v120
	v_exp_f32_e32 v121, v121
	v_exp_f32_e32 v114, v114
	v_exp_f32_e32 v115, v115
	v_exp_f32_e32 v116, v116
	v_exp_f32_e32 v117, v117
	v_pk_add_f32 v[118:119], v[118:119], 1.0 op_sel_hi:[1,0]
	v_pk_add_f32 v[120:121], v[120:121], 1.0 op_sel_hi:[1,0]
	v_pk_add_f32 v[114:115], v[114:115], 1.0 op_sel_hi:[1,0]
	v_pk_add_f32 v[116:117], v[116:117], 1.0 op_sel_hi:[1,0]
	v_rcp_f32_e32 v118, v118
	v_rcp_f32_e32 v119, v119
	v_rcp_f32_e32 v120, v120
	v_rcp_f32_e32 v121, v121
	v_rcp_f32_e32 v114, v114
	v_rcp_f32_e32 v115, v115
	v_rcp_f32_e32 v116, v116
	v_rcp_f32_e32 v117, v117
	v_cvt_pk_bf16_f32 v182, v118, v119
	v_cvt_pk_bf16_f32 v183, v120, v121
	v_cvt_pk_bf16_f32 v184, v114, v115
	v_cvt_pk_bf16_f32 v185, v116, v117
	global_store_dwordx4 v[176:177], v[182:185], off offset:1024
	v_pk_fma_f32 v[110:111], v[110:111], s[100:101], v[142:143]
	v_pk_fma_f32 v[112:113], v[112:113], s[100:101], v[144:145]
	v_pk_fma_f32 v[106:107], v[106:107], s[100:101], v[138:139]
	v_pk_fma_f32 v[108:109], v[108:109], s[100:101], v[140:141]
	v_exp_f32_e32 v110, v110
	v_exp_f32_e32 v111, v111
	v_exp_f32_e32 v112, v112
	v_exp_f32_e32 v113, v113
	v_exp_f32_e32 v106, v106
	v_exp_f32_e32 v107, v107
	v_exp_f32_e32 v108, v108
	v_exp_f32_e32 v109, v109
	v_pk_add_f32 v[110:111], v[110:111], 1.0 op_sel_hi:[1,0]
	v_pk_add_f32 v[112:113], v[112:113], 1.0 op_sel_hi:[1,0]
	v_pk_add_f32 v[106:107], v[106:107], 1.0 op_sel_hi:[1,0]
	v_pk_add_f32 v[108:109], v[108:109], 1.0 op_sel_hi:[1,0]
	v_rcp_f32_e32 v110, v110
	v_rcp_f32_e32 v111, v111
	v_rcp_f32_e32 v112, v112
	v_rcp_f32_e32 v113, v113
	v_rcp_f32_e32 v106, v106
	v_rcp_f32_e32 v107, v107
	v_rcp_f32_e32 v108, v108
	v_rcp_f32_e32 v109, v109
	v_cvt_pk_bf16_f32 v146, v110, v111
	v_cvt_pk_bf16_f32 v147, v112, v113
	v_cvt_pk_bf16_f32 v148, v106, v107
	v_cvt_pk_bf16_f32 v149, v108, v109
	global_store_dwordx4 v[176:177], v[146:149], off offset:2048
	v_pk_fma_f32 v[102:103], v[102:103], s[100:101], v[134:135]
	v_pk_fma_f32 v[104:105], v[104:105], s[100:101], v[136:137]
	v_pk_fma_f32 v[98:99], v[98:99], s[100:101], v[130:131]
	v_pk_fma_f32 v[100:101], v[100:101], s[100:101], v[132:133]
	v_exp_f32_e32 v102, v102
	v_exp_f32_e32 v103, v103
	v_exp_f32_e32 v104, v104
	v_exp_f32_e32 v105, v105
	v_exp_f32_e32 v98, v98
	v_exp_f32_e32 v99, v99
	v_exp_f32_e32 v100, v100
	v_exp_f32_e32 v101, v101
	v_pk_add_f32 v[102:103], v[102:103], 1.0 op_sel_hi:[1,0]
	v_pk_add_f32 v[104:105], v[104:105], 1.0 op_sel_hi:[1,0]
	v_pk_add_f32 v[98:99], v[98:99], 1.0 op_sel_hi:[1,0]
	v_pk_add_f32 v[100:101], v[100:101], 1.0 op_sel_hi:[1,0]
	v_rcp_f32_e32 v102, v102
	v_rcp_f32_e32 v103, v103
	v_rcp_f32_e32 v104, v104
	v_rcp_f32_e32 v105, v105
	v_rcp_f32_e32 v98, v98
	v_rcp_f32_e32 v99, v99
	v_rcp_f32_e32 v100, v100
	v_rcp_f32_e32 v101, v101
	v_cvt_pk_bf16_f32 v182, v102, v103
	v_cvt_pk_bf16_f32 v183, v104, v105
	v_cvt_pk_bf16_f32 v184, v98, v99
	v_cvt_pk_bf16_f32 v185, v100, v101
	global_store_dwordx4 v[176:177], v[182:185], off offset:3072
	v_lshl_add_u64 v[176:177], v[176:177], 0, s[14:15]
	v_pk_fma_f32 v[94:95], v[94:95], s[100:101], v[142:143]
	v_pk_fma_f32 v[96:97], v[96:97], s[100:101], v[144:145]
	v_pk_fma_f32 v[90:91], v[90:91], s[100:101], v[138:139]
	v_pk_fma_f32 v[92:93], v[92:93], s[100:101], v[140:141]
	v_exp_f32_e32 v94, v94
	v_exp_f32_e32 v95, v95
	v_exp_f32_e32 v96, v96
	v_exp_f32_e32 v97, v97
	v_exp_f32_e32 v90, v90
	v_exp_f32_e32 v91, v91
	v_exp_f32_e32 v92, v92
	v_exp_f32_e32 v93, v93
	v_pk_add_f32 v[94:95], v[94:95], 1.0 op_sel_hi:[1,0]
	v_pk_add_f32 v[96:97], v[96:97], 1.0 op_sel_hi:[1,0]
	v_pk_add_f32 v[90:91], v[90:91], 1.0 op_sel_hi:[1,0]
	v_pk_add_f32 v[92:93], v[92:93], 1.0 op_sel_hi:[1,0]
	v_rcp_f32_e32 v94, v94
	v_rcp_f32_e32 v95, v95
	v_rcp_f32_e32 v96, v96
	v_rcp_f32_e32 v97, v97
	v_rcp_f32_e32 v90, v90
	v_rcp_f32_e32 v91, v91
	v_rcp_f32_e32 v92, v92
	v_rcp_f32_e32 v93, v93
	v_cvt_pk_bf16_f32 v146, v94, v95
	v_cvt_pk_bf16_f32 v147, v96, v97
	v_cvt_pk_bf16_f32 v148, v90, v91
	v_cvt_pk_bf16_f32 v149, v92, v93
	global_store_dwordx4 v[176:177], v[146:149], off offset:0
	v_pk_fma_f32 v[86:87], v[86:87], s[100:101], v[134:135]
	v_pk_fma_f32 v[88:89], v[88:89], s[100:101], v[136:137]
	v_pk_fma_f32 v[82:83], v[82:83], s[100:101], v[130:131]
	v_pk_fma_f32 v[84:85], v[84:85], s[100:101], v[132:133]
	v_exp_f32_e32 v86, v86
	v_exp_f32_e32 v87, v87
	v_exp_f32_e32 v88, v88
	v_exp_f32_e32 v89, v89
	v_exp_f32_e32 v82, v82
	v_exp_f32_e32 v83, v83
	v_exp_f32_e32 v84, v84
	v_exp_f32_e32 v85, v85
	v_pk_add_f32 v[86:87], v[86:87], 1.0 op_sel_hi:[1,0]
	v_pk_add_f32 v[88:89], v[88:89], 1.0 op_sel_hi:[1,0]
	v_pk_add_f32 v[82:83], v[82:83], 1.0 op_sel_hi:[1,0]
	v_pk_add_f32 v[84:85], v[84:85], 1.0 op_sel_hi:[1,0]
	v_rcp_f32_e32 v86, v86
	v_rcp_f32_e32 v87, v87
	v_rcp_f32_e32 v88, v88
	v_rcp_f32_e32 v89, v89
	v_rcp_f32_e32 v82, v82
	v_rcp_f32_e32 v83, v83
	v_rcp_f32_e32 v84, v84
	v_rcp_f32_e32 v85, v85
	v_cvt_pk_bf16_f32 v182, v86, v87
	v_cvt_pk_bf16_f32 v183, v88, v89
	v_cvt_pk_bf16_f32 v184, v82, v83
	v_cvt_pk_bf16_f32 v185, v84, v85
	global_store_dwordx4 v[176:177], v[182:185], off offset:1024
	v_pk_fma_f32 v[78:79], v[78:79], s[100:101], v[142:143]
	v_pk_fma_f32 v[80:81], v[80:81], s[100:101], v[144:145]
	v_pk_fma_f32 v[74:75], v[74:75], s[100:101], v[138:139]
	v_pk_fma_f32 v[76:77], v[76:77], s[100:101], v[140:141]
	v_exp_f32_e32 v78, v78
	v_exp_f32_e32 v79, v79
	v_exp_f32_e32 v80, v80
	v_exp_f32_e32 v81, v81
	v_exp_f32_e32 v74, v74
	v_exp_f32_e32 v75, v75
	v_exp_f32_e32 v76, v76
	v_exp_f32_e32 v77, v77
	v_pk_add_f32 v[78:79], v[78:79], 1.0 op_sel_hi:[1,0]
	v_pk_add_f32 v[80:81], v[80:81], 1.0 op_sel_hi:[1,0]
	v_pk_add_f32 v[74:75], v[74:75], 1.0 op_sel_hi:[1,0]
	v_pk_add_f32 v[76:77], v[76:77], 1.0 op_sel_hi:[1,0]
	v_rcp_f32_e32 v78, v78
	v_rcp_f32_e32 v79, v79
	v_rcp_f32_e32 v80, v80
	v_rcp_f32_e32 v81, v81
	v_rcp_f32_e32 v74, v74
	v_rcp_f32_e32 v75, v75
	v_rcp_f32_e32 v76, v76
	v_rcp_f32_e32 v77, v77
	v_cvt_pk_bf16_f32 v146, v78, v79
	v_cvt_pk_bf16_f32 v147, v80, v81
	v_cvt_pk_bf16_f32 v148, v74, v75
	v_cvt_pk_bf16_f32 v149, v76, v77
	global_store_dwordx4 v[176:177], v[146:149], off offset:2048
	v_pk_fma_f32 v[70:71], v[70:71], s[100:101], v[134:135]
	v_pk_fma_f32 v[72:73], v[72:73], s[100:101], v[136:137]
	v_pk_fma_f32 v[66:67], v[66:67], s[100:101], v[130:131]
	v_pk_fma_f32 v[68:69], v[68:69], s[100:101], v[132:133]
	v_exp_f32_e32 v70, v70
	v_exp_f32_e32 v71, v71
	v_exp_f32_e32 v72, v72
	v_exp_f32_e32 v73, v73
	v_exp_f32_e32 v66, v66
	v_exp_f32_e32 v67, v67
	v_exp_f32_e32 v68, v68
	v_exp_f32_e32 v69, v69
	v_pk_add_f32 v[70:71], v[70:71], 1.0 op_sel_hi:[1,0]
	v_pk_add_f32 v[72:73], v[72:73], 1.0 op_sel_hi:[1,0]
	v_pk_add_f32 v[66:67], v[66:67], 1.0 op_sel_hi:[1,0]
	v_pk_add_f32 v[68:69], v[68:69], 1.0 op_sel_hi:[1,0]
	v_rcp_f32_e32 v70, v70
	v_rcp_f32_e32 v71, v71
	v_rcp_f32_e32 v72, v72
	v_rcp_f32_e32 v73, v73
	v_rcp_f32_e32 v66, v66
	v_rcp_f32_e32 v67, v67
	v_rcp_f32_e32 v68, v68
	v_rcp_f32_e32 v69, v69
	v_cvt_pk_bf16_f32 v182, v70, v71
	v_cvt_pk_bf16_f32 v183, v72, v73
	v_cvt_pk_bf16_f32 v184, v66, v67
	v_cvt_pk_bf16_f32 v185, v68, v69
	global_store_dwordx4 v[176:177], v[182:185], off offset:3072
	v_lshl_add_u64 v[176:177], v[176:177], 0, s[14:15]
	v_pk_fma_f32 v[62:63], v[62:63], s[100:101], v[142:143]
	v_pk_fma_f32 v[64:65], v[64:65], s[100:101], v[144:145]
	v_pk_fma_f32 v[58:59], v[58:59], s[100:101], v[138:139]
	v_pk_fma_f32 v[60:61], v[60:61], s[100:101], v[140:141]
	v_exp_f32_e32 v62, v62
	v_exp_f32_e32 v63, v63
	v_exp_f32_e32 v64, v64
	v_exp_f32_e32 v65, v65
	v_exp_f32_e32 v58, v58
	v_exp_f32_e32 v59, v59
	v_exp_f32_e32 v60, v60
	v_exp_f32_e32 v61, v61
	v_pk_add_f32 v[62:63], v[62:63], 1.0 op_sel_hi:[1,0]
	v_pk_add_f32 v[64:65], v[64:65], 1.0 op_sel_hi:[1,0]
	v_pk_add_f32 v[58:59], v[58:59], 1.0 op_sel_hi:[1,0]
	v_pk_add_f32 v[60:61], v[60:61], 1.0 op_sel_hi:[1,0]
	v_rcp_f32_e32 v62, v62
	v_rcp_f32_e32 v63, v63
	v_rcp_f32_e32 v64, v64
	v_rcp_f32_e32 v65, v65
	v_rcp_f32_e32 v58, v58
	v_rcp_f32_e32 v59, v59
	v_rcp_f32_e32 v60, v60
	v_rcp_f32_e32 v61, v61
	v_cvt_pk_bf16_f32 v146, v62, v63
	v_cvt_pk_bf16_f32 v147, v64, v65
	v_cvt_pk_bf16_f32 v148, v58, v59
	v_cvt_pk_bf16_f32 v149, v60, v61
	global_store_dwordx4 v[176:177], v[146:149], off offset:0
	v_pk_fma_f32 v[54:55], v[54:55], s[100:101], v[134:135]
	v_pk_fma_f32 v[56:57], v[56:57], s[100:101], v[136:137]
	v_pk_fma_f32 v[50:51], v[50:51], s[100:101], v[130:131]
	v_pk_fma_f32 v[52:53], v[52:53], s[100:101], v[132:133]
	v_exp_f32_e32 v54, v54
	v_exp_f32_e32 v55, v55
	v_exp_f32_e32 v56, v56
	v_exp_f32_e32 v57, v57
	v_exp_f32_e32 v50, v50
	v_exp_f32_e32 v51, v51
	v_exp_f32_e32 v52, v52
	v_exp_f32_e32 v53, v53
	v_pk_add_f32 v[54:55], v[54:55], 1.0 op_sel_hi:[1,0]
	v_pk_add_f32 v[56:57], v[56:57], 1.0 op_sel_hi:[1,0]
	v_pk_add_f32 v[50:51], v[50:51], 1.0 op_sel_hi:[1,0]
	v_pk_add_f32 v[52:53], v[52:53], 1.0 op_sel_hi:[1,0]
	v_rcp_f32_e32 v54, v54
	v_rcp_f32_e32 v55, v55
	v_rcp_f32_e32 v56, v56
	v_rcp_f32_e32 v57, v57
	v_rcp_f32_e32 v50, v50
	v_rcp_f32_e32 v51, v51
	v_rcp_f32_e32 v52, v52
	v_rcp_f32_e32 v53, v53
	v_cvt_pk_bf16_f32 v182, v54, v55
	v_cvt_pk_bf16_f32 v183, v56, v57
	v_cvt_pk_bf16_f32 v184, v50, v51
	v_cvt_pk_bf16_f32 v185, v52, v53
	global_store_dwordx4 v[176:177], v[182:185], off offset:1024
	v_pk_fma_f32 v[46:47], v[46:47], s[100:101], v[142:143]
	v_pk_fma_f32 v[48:49], v[48:49], s[100:101], v[144:145]
	v_pk_fma_f32 v[42:43], v[42:43], s[100:101], v[138:139]
	v_pk_fma_f32 v[44:45], v[44:45], s[100:101], v[140:141]
	v_exp_f32_e32 v46, v46
	v_exp_f32_e32 v47, v47
	v_exp_f32_e32 v48, v48
	v_exp_f32_e32 v49, v49
	v_exp_f32_e32 v42, v42
	v_exp_f32_e32 v43, v43
	v_exp_f32_e32 v44, v44
	v_exp_f32_e32 v45, v45
	v_pk_add_f32 v[46:47], v[46:47], 1.0 op_sel_hi:[1,0]
	v_pk_add_f32 v[48:49], v[48:49], 1.0 op_sel_hi:[1,0]
	v_pk_add_f32 v[42:43], v[42:43], 1.0 op_sel_hi:[1,0]
	v_pk_add_f32 v[44:45], v[44:45], 1.0 op_sel_hi:[1,0]
	v_rcp_f32_e32 v46, v46
	v_rcp_f32_e32 v47, v47
	v_rcp_f32_e32 v48, v48
	v_rcp_f32_e32 v49, v49
	v_rcp_f32_e32 v42, v42
	v_rcp_f32_e32 v43, v43
	v_rcp_f32_e32 v44, v44
	v_rcp_f32_e32 v45, v45
	v_cvt_pk_bf16_f32 v146, v46, v47
	v_cvt_pk_bf16_f32 v147, v48, v49
	v_cvt_pk_bf16_f32 v148, v42, v43
	v_cvt_pk_bf16_f32 v149, v44, v45
	global_store_dwordx4 v[176:177], v[146:149], off offset:2048
	v_pk_fma_f32 v[38:39], v[38:39], s[100:101], v[134:135]
	v_pk_fma_f32 v[40:41], v[40:41], s[100:101], v[136:137]
	v_pk_fma_f32 v[34:35], v[34:35], s[100:101], v[130:131]
	v_pk_fma_f32 v[36:37], v[36:37], s[100:101], v[132:133]
	v_exp_f32_e32 v38, v38
	v_exp_f32_e32 v39, v39
	v_exp_f32_e32 v40, v40
	v_exp_f32_e32 v41, v41
	v_exp_f32_e32 v34, v34
	v_exp_f32_e32 v35, v35
	v_exp_f32_e32 v36, v36
	v_exp_f32_e32 v37, v37
	v_pk_add_f32 v[38:39], v[38:39], 1.0 op_sel_hi:[1,0]
	v_pk_add_f32 v[40:41], v[40:41], 1.0 op_sel_hi:[1,0]
	v_pk_add_f32 v[34:35], v[34:35], 1.0 op_sel_hi:[1,0]
	v_pk_add_f32 v[36:37], v[36:37], 1.0 op_sel_hi:[1,0]
	v_rcp_f32_e32 v38, v38
	v_rcp_f32_e32 v39, v39
	v_rcp_f32_e32 v40, v40
	v_rcp_f32_e32 v41, v41
	v_rcp_f32_e32 v34, v34
	v_rcp_f32_e32 v35, v35
	v_rcp_f32_e32 v36, v36
	v_rcp_f32_e32 v37, v37
	v_cvt_pk_bf16_f32 v182, v38, v39
	v_cvt_pk_bf16_f32 v183, v40, v41
	v_cvt_pk_bf16_f32 v184, v34, v35
	v_cvt_pk_bf16_f32 v185, v36, v37
	global_store_dwordx4 v[176:177], v[182:185], off offset:3072
	v_lshl_add_u64 v[176:177], v[176:177], 0, s[14:15]
	v_pk_fma_f32 v[30:31], v[30:31], s[100:101], v[142:143]
	v_pk_fma_f32 v[32:33], v[32:33], s[100:101], v[144:145]
	v_pk_fma_f32 v[26:27], v[26:27], s[100:101], v[138:139]
	v_pk_fma_f32 v[28:29], v[28:29], s[100:101], v[140:141]
	v_exp_f32_e32 v30, v30
	v_exp_f32_e32 v31, v31
	v_exp_f32_e32 v32, v32
	v_exp_f32_e32 v33, v33
	v_exp_f32_e32 v26, v26
	v_exp_f32_e32 v27, v27
	v_exp_f32_e32 v28, v28
	v_exp_f32_e32 v29, v29
	v_pk_add_f32 v[30:31], v[30:31], 1.0 op_sel_hi:[1,0]
	v_pk_add_f32 v[32:33], v[32:33], 1.0 op_sel_hi:[1,0]
	v_pk_add_f32 v[26:27], v[26:27], 1.0 op_sel_hi:[1,0]
	v_pk_add_f32 v[28:29], v[28:29], 1.0 op_sel_hi:[1,0]
	v_rcp_f32_e32 v30, v30
	v_rcp_f32_e32 v31, v31
	v_rcp_f32_e32 v32, v32
	v_rcp_f32_e32 v33, v33
	v_rcp_f32_e32 v26, v26
	v_rcp_f32_e32 v27, v27
	v_rcp_f32_e32 v28, v28
	v_rcp_f32_e32 v29, v29
	v_cvt_pk_bf16_f32 v146, v30, v31
	v_cvt_pk_bf16_f32 v147, v32, v33
	v_cvt_pk_bf16_f32 v148, v26, v27
	v_cvt_pk_bf16_f32 v149, v28, v29
	global_store_dwordx4 v[176:177], v[146:149], off offset:0
	v_pk_fma_f32 v[22:23], v[22:23], s[100:101], v[134:135]
	v_pk_fma_f32 v[24:25], v[24:25], s[100:101], v[136:137]
	v_pk_fma_f32 v[18:19], v[18:19], s[100:101], v[130:131]
	v_pk_fma_f32 v[20:21], v[20:21], s[100:101], v[132:133]
	v_exp_f32_e32 v22, v22
	v_exp_f32_e32 v23, v23
	v_exp_f32_e32 v24, v24
	v_exp_f32_e32 v25, v25
	v_exp_f32_e32 v18, v18
	v_exp_f32_e32 v19, v19
	v_exp_f32_e32 v20, v20
	v_exp_f32_e32 v21, v21
	v_pk_add_f32 v[22:23], v[22:23], 1.0 op_sel_hi:[1,0]
	v_pk_add_f32 v[24:25], v[24:25], 1.0 op_sel_hi:[1,0]
	v_pk_add_f32 v[18:19], v[18:19], 1.0 op_sel_hi:[1,0]
	v_pk_add_f32 v[20:21], v[20:21], 1.0 op_sel_hi:[1,0]
	v_rcp_f32_e32 v22, v22
	v_rcp_f32_e32 v23, v23
	v_rcp_f32_e32 v24, v24
	v_rcp_f32_e32 v25, v25
	v_rcp_f32_e32 v18, v18
	v_rcp_f32_e32 v19, v19
	v_rcp_f32_e32 v20, v20
	v_rcp_f32_e32 v21, v21
	v_cvt_pk_bf16_f32 v182, v22, v23
	v_cvt_pk_bf16_f32 v183, v24, v25
	v_cvt_pk_bf16_f32 v184, v18, v19
	v_cvt_pk_bf16_f32 v185, v20, v21
	global_store_dwordx4 v[176:177], v[182:185], off offset:1024
	v_pk_fma_f32 v[14:15], v[14:15], s[100:101], v[142:143]
	v_pk_fma_f32 v[16:17], v[16:17], s[100:101], v[144:145]
	v_pk_fma_f32 v[10:11], v[10:11], s[100:101], v[138:139]
	v_pk_fma_f32 v[12:13], v[12:13], s[100:101], v[140:141]
	v_exp_f32_e32 v14, v14
	v_exp_f32_e32 v15, v15
	v_exp_f32_e32 v16, v16
	v_exp_f32_e32 v17, v17
	v_exp_f32_e32 v10, v10
	v_exp_f32_e32 v11, v11
	v_exp_f32_e32 v12, v12
	v_exp_f32_e32 v13, v13
	v_pk_add_f32 v[14:15], v[14:15], 1.0 op_sel_hi:[1,0]
	v_pk_add_f32 v[16:17], v[16:17], 1.0 op_sel_hi:[1,0]
	v_pk_add_f32 v[10:11], v[10:11], 1.0 op_sel_hi:[1,0]
	v_pk_add_f32 v[12:13], v[12:13], 1.0 op_sel_hi:[1,0]
	v_rcp_f32_e32 v14, v14
	v_rcp_f32_e32 v15, v15
	v_rcp_f32_e32 v16, v16
	v_rcp_f32_e32 v17, v17
	v_rcp_f32_e32 v10, v10
	v_rcp_f32_e32 v11, v11
	v_rcp_f32_e32 v12, v12
	v_rcp_f32_e32 v13, v13
	v_cvt_pk_bf16_f32 v146, v14, v15
	v_cvt_pk_bf16_f32 v147, v16, v17
	v_cvt_pk_bf16_f32 v148, v10, v11
	v_cvt_pk_bf16_f32 v149, v12, v13
	global_store_dwordx4 v[176:177], v[146:149], off offset:2048
	v_pk_fma_f32 v[6:7], v[6:7], s[100:101], v[134:135]
	v_pk_fma_f32 v[8:9], v[8:9], s[100:101], v[136:137]
	v_pk_fma_f32 v[2:3], v[2:3], s[100:101], v[130:131]
	v_pk_fma_f32 v[4:5], v[4:5], s[100:101], v[132:133]
	v_exp_f32_e32 v6, v6
	v_exp_f32_e32 v7, v7
	v_exp_f32_e32 v8, v8
	v_exp_f32_e32 v9, v9
	v_exp_f32_e32 v2, v2
	v_exp_f32_e32 v3, v3
	v_exp_f32_e32 v4, v4
	v_exp_f32_e32 v5, v5
	v_pk_add_f32 v[6:7], v[6:7], 1.0 op_sel_hi:[1,0]
	v_pk_add_f32 v[8:9], v[8:9], 1.0 op_sel_hi:[1,0]
	v_pk_add_f32 v[2:3], v[2:3], 1.0 op_sel_hi:[1,0]
	v_pk_add_f32 v[4:5], v[4:5], 1.0 op_sel_hi:[1,0]
	v_rcp_f32_e32 v6, v6
	v_rcp_f32_e32 v7, v7
	v_rcp_f32_e32 v8, v8
	v_rcp_f32_e32 v9, v9
	v_rcp_f32_e32 v2, v2
	v_rcp_f32_e32 v3, v3
	v_rcp_f32_e32 v4, v4
	v_rcp_f32_e32 v5, v5
	v_cvt_pk_bf16_f32 v182, v6, v7
	v_cvt_pk_bf16_f32 v183, v8, v9
	v_cvt_pk_bf16_f32 v184, v2, v3
	v_cvt_pk_bf16_f32 v185, v4, v5
	global_store_dwordx4 v[176:177], v[182:185], off offset:3072
	s_branch .LBB0_184
